# two-group attention loop + lazy row-sum (running pair accumulator, cross-lane reduction once per map) to cut softmax-segment issue slots
# speedup vs baseline: 1.0153x; 1.0027x over previous
; #define A128_SBAR() __builtin_amdgcn_sched_barrier(0)
; #define A128_PK4(P, BASE, OUT) do { u32x4 w = {cvt_pk_bf16(P[BASE + 0], P[BASE + 1]), cvt_pk_bf16(P[BASE + 2], P[BASE + 3]), cvt_pk_bf16(P[BASE + 4], P[BASE + 5]), cvt_pk_bf16(P[BASE + 6], P[BASE + 7])}; \
;     OUT = __builtin_bit_cast(bf16x8, w); } while (0)
; #define A128_SWAIT() asm volatile("s_waitcnt vmcnt(3)" ::: "memory")
; __device__ __forceinline__ void finishSM(f32x16& p0, f32x16& p1, float alpha, float& l_reg, bf16x8& pa0, bf16x8& pa1, bf16x8& pa2, bf16x8& pa3) {
; #pragma unroll
;   for (int r = 0; r < 16; ++r) p1[r] = __builtin_amdgcn_exp2f(p1[r]);
;   typedef float f32x8_ __attribute__((ext_vector_type(8))); typedef float f32x2_ __attribute__((ext_vector_type(2)));
;   const f32x16 s16_ = p0 + p1; const f32x8_ s8_ = s16_.lo + s16_.hi; const f32x4 s4_ = s8_.lo + s8_.hi; const f32x2_ s2_ = s4_.lo + s4_.hi;
;   float ps = s2_.x + s2_.y;
;   { auto rr = __builtin_amdgcn_permlane32_swap(__float_as_uint(ps), __float_as_uint(ps), false, false); ps = __uint_as_float(rr[0]) + __uint_as_float(rr[1]); }
;   l_reg = l_reg * alpha + ps;
;     ...
;   A128_PK4(p0, 0, pa0); A128_PK4(p0, 8, pa1); A128_PK4(p1, 0, pa2); A128_PK4(p1, 8, pa3);
;     ...
; }
; __device__ __forceinline__ void unit(const bf16* __restrict__ Qb0, const bf16* __restrict__ Kh0, const bf16* __restrict__ Vh, bf16_t* Ob, int seq, char* lds, const int tid_in, const float lam, const float onem, const float* __restrict__ subw, const float* __restrict__ kmb  ) {
;     ...
;   for (int j = 1; j + 1 < NT; j += 2) {
;     A128_SBAR(); qkt(pB0, pB1, K_lds + SHM_K, qr, r32, hi);
;     finishSM(pA0, pA1, alA, l_reg, pa0, pa1, pa2, pa3); A128_SBAR();
;     A128_SLOAD(1, (j + 2) * KVBLK); A128_SBAR();
;     pv_d0(o, vb0, pa0, pa1, pa2, pa3); partialSM(pB0, pB1, m_reg, mnB, alB, nomax);
;     __syncthreads(); A128_SWAIT(); A128_SWRITE(0, 0);
;     if (!nomax) A128_RESC(alB); __syncthreads();
;     A128_SBAR(); qkt(pA0, pA1, K_lds, qr, r32, hi);
;     finishSM(pB0, pB1, alB, l_reg, pa0, pa1, pa2, pa3); A128_SBAR();
;     if (j + 3 < NT) A128_SLOAD(0, (j + 3) * KVBLK); A128_SBAR();
;     pv_d0(o, vb0 + (int)SHM_V, pa0, pa1, pa2, pa3); partialSM(pA0, pA1, m_reg, mnA, alA, nomax);
;     __syncthreads(); A128_SWAIT(); A128_SWRITE(1, 1);
;     if (!nomax) A128_RESC(alA); __syncthreads();
;   }
.Lfa_g0:
	global_load_dwordx4 v[152:155], v198, s[100:101]
	global_load_dwordx4 v[148:151], v199, s[100:101]
	s_add_u32 s100, s100, 0x1a0000
	s_addc_u32 s101, s101, 0
	global_load_dwordx4 v[232:235], v198, s[100:101]
	global_load_dwordx4 v[236:239], v199, s[100:101]
	global_load_dwordx4 v[240:243], v0, s[100:101] offset:2048
	s_add_u32 s100, s100, 0x1a0000
	s_addc_u32 s101, s101, 0
	v_exp_f32_e32 v80, v80
	v_exp_f32_e32 v81, v81
	v_exp_f32_e32 v82, v82
	v_exp_f32_e32 v83, v83
	v_exp_f32_e32 v84, v84
	v_exp_f32_e32 v85, v85
	v_exp_f32_e32 v86, v86
	v_exp_f32_e32 v87, v87
	v_exp_f32_e32 v88, v88
	v_exp_f32_e32 v89, v89
	v_exp_f32_e32 v90, v90
	v_exp_f32_e32 v91, v91
	v_exp_f32_e32 v92, v92
	v_exp_f32_e32 v93, v93
	v_exp_f32_e32 v94, v94
	v_exp_f32_e32 v95, v95
	v_pk_add_f32 v[2:3], v[178:179], v[80:81]
	v_pk_add_f32 v[4:5], v[176:177], v[82:83]
	v_pk_add_f32 v[6:7], v[174:175], v[84:85]
	v_pk_add_f32 v[8:9], v[172:173], v[86:87]
	v_pk_add_f32 v[10:11], v[170:171], v[88:89]
	v_pk_add_f32 v[12:13], v[168:169], v[90:91]
	v_pk_add_f32 v[14:15], v[164:165], v[92:93]
	v_pk_add_f32 v[194:195], v[162:163], v[94:95]
	v_pk_add_f32 v[2:3], v[2:3], v[10:11]
	v_pk_add_f32 v[4:5], v[4:5], v[12:13]
	v_pk_add_f32 v[6:7], v[6:7], v[14:15]
	v_pk_add_f32 v[8:9], v[8:9], v[194:195]
	v_pk_add_f32 v[2:3], v[2:3], v[6:7]
	v_pk_add_f32 v[4:5], v[4:5], v[8:9]
	s_nop 0
	v_pk_add_f32 v[2:3], v[2:3], v[4:5]
	s_nop 0
	v_add_f32_e32 v2, v2, v3
	s_nop 0
	v_mov_b32_e32 v3, v2
	s_nop 1
	v_permlane32_swap_b32_e32 v2, v3
	s_nop 1
	v_add_f32_e32 v2, v2, v3
	s_nop 0
	v_add_f32_e32 v186, v186, v2
	v_cvt_pk_bf16_f32 v2, v80, v81
	v_cvt_pk_bf16_f32 v3, v82, v83
	v_cvt_pk_bf16_f32 v4, v84, v85
	v_cvt_pk_bf16_f32 v5, v86, v87
	v_cvt_pk_bf16_f32 v6, v88, v89
	v_cvt_pk_bf16_f32 v7, v90, v91
	v_cvt_pk_bf16_f32 v8, v92, v93
	v_cvt_pk_bf16_f32 v9, v94, v95
	s_nop 0
	v_cvt_pk_bf16_f32 v80, v178, v179
	v_cvt_pk_bf16_f32 v81, v176, v177
	v_cvt_pk_bf16_f32 v82, v174, v175
	v_cvt_pk_bf16_f32 v83, v172, v173
	v_cvt_pk_bf16_f32 v84, v170, v171
	v_cvt_pk_bf16_f32 v85, v168, v169
	v_cvt_pk_bf16_f32 v86, v164, v165
	v_cvt_pk_bf16_f32 v87, v162, v163
	v_mov_b32_e32 v88, v2
	v_mov_b32_e32 v89, v3
	v_mov_b32_e32 v90, v4
	v_mov_b32_e32 v91, v5
	v_mov_b32_e32 v92, v6
	v_mov_b32_e32 v93, v7
	v_mov_b32_e32 v94, v8
	v_mov_b32_e32 v95, v9
	v_mov_b32_e32 v14, 0
	v_mov_b32_e32 v15, 0
.Lfa_loop:
	s_barrier
	s_setprio 1
	ds_read_b128 v[2:5], v204 offset:40960
	ds_read_b128 v[6:9], v204 offset:45056
	ds_read_b128 v[10:13], v205 offset:40960
	ds_read_b128 v[162:165], v205 offset:45056
	s_waitcnt lgkmcnt(2)
	v_mfma_f32_32x32x16_bf16 v[112:127], v[2:5], v[140:143], 0
	ds_read_b128 v[168:171], v192 offset:40960
	ds_read_b128 v[172:175], v192 offset:45056
	v_mfma_f32_32x32x16_bf16 v[96:111], v[6:9], v[140:143], 0
	ds_read_b128 v[176:179], v193 offset:40960
	ds_read_b128 v[194:197], v193 offset:45056
	s_waitcnt lgkmcnt(4)
	v_mfma_f32_32x32x16_bf16 v[112:127], v[10:13], v[136:139], v[112:127]
	ds_read_b64_tr_b16 v[210:211], v190 offset:0x0
	ds_read_b64_tr_b16 v[212:213], v190 offset:0x800
	ds_read_b64_tr_b16 v[214:215], v190 offset:0x1000
	v_mfma_f32_32x32x16_bf16 v[96:111], v[162:165], v[136:139], v[96:111]
	ds_read_b64_tr_b16 v[216:217], v190 offset:0x1800
	ds_read_b64_tr_b16 v[244:245], v190 offset:0x2000
	ds_read_b64_tr_b16 v[246:247], v190 offset:0x2800
	s_waitcnt lgkmcnt(8)
	v_mfma_f32_32x32x16_bf16 v[112:127], v[168:171], v[132:135], v[112:127]
	ds_read_b64_tr_b16 v[248:249], v190 offset:0x3000
	ds_read_b64_tr_b16 v[250:251], v190 offset:0x3800
	v_mfma_f32_32x32x16_bf16 v[96:111], v[172:175], v[132:135], v[96:111]
	ds_read_b64_tr_b16 v[2:3], v190 offset:0x200
	ds_read_b64_tr_b16 v[4:5], v190 offset:0xa00
	ds_read_b64_tr_b16 v[6:7], v190 offset:0x1200
	s_waitcnt lgkmcnt(11)
	v_mfma_f32_32x32x16_bf16 v[112:127], v[176:179], v[128:131], v[112:127]
	ds_read_b64_tr_b16 v[8:9], v190 offset:0x1a00
	ds_read_b64_tr_b16 v[10:11], v190 offset:0x2200
	ds_read_b64_tr_b16 v[12:13], v190 offset:0x2a00
	v_mfma_f32_32x32x16_bf16 v[96:111], v[194:197], v[128:131], v[96:111]
	ds_read_b64_tr_b16 v[162:163], v190 offset:0x3200
	ds_read_b64_tr_b16 v[164:165], v190 offset:0x3a00
	s_waitcnt vmcnt(3)
	ds_write_b128 v203, v[144:147] offset:32768
	ds_write_b128 v191, v[152:155] offset:16384
	ds_write_b128 v202, v[148:151] offset:16384
	s_waitcnt lgkmcnt(11)
	v_mfma_f32_32x32x16_bf16 v[16:31], v[80:83], v[210:213], v[16:31]
	ds_read_b64_tr_b16 v[210:211], v190 offset:0x400
	ds_read_b64_tr_b16 v[212:213], v190 offset:0xc00
	v_mfma_f32_32x32x16_bf16 v[16:31], v[84:87], v[214:217], v[16:31]
	ds_read_b64_tr_b16 v[214:215], v190 offset:0x1400
	ds_read_b64_tr_b16 v[216:217], v190 offset:0x1c00
	v_mfma_f32_32x32x16_bf16 v[16:31], v[88:91], v[244:247], v[16:31]
	ds_read_b64_tr_b16 v[244:245], v190 offset:0x2400
	ds_read_b64_tr_b16 v[246:247], v190 offset:0x2c00
	v_mfma_f32_32x32x16_bf16 v[16:31], v[92:95], v[248:251], v[16:31]
	ds_read_b64_tr_b16 v[248:249], v190 offset:0x3400
	ds_read_b64_tr_b16 v[250:251], v190 offset:0x3c00
	s_waitcnt lgkmcnt(11)
	v_mfma_f32_32x32x16_bf16 v[32:47], v[80:83], v[2:5], v[32:47]
	ds_read_b64_tr_b16 v[2:3], v190 offset:0x600
	ds_read_b64_tr_b16 v[4:5], v190 offset:0xe00
	v_mfma_f32_32x32x16_bf16 v[32:47], v[84:87], v[6:9], v[32:47]
	ds_read_b64_tr_b16 v[6:7], v190 offset:0x1600
	ds_read_b64_tr_b16 v[8:9], v190 offset:0x1e00
	v_mfma_f32_32x32x16_bf16 v[32:47], v[88:91], v[10:13], v[32:47]
	ds_read_b64_tr_b16 v[10:11], v190 offset:0x2600
	ds_read_b64_tr_b16 v[12:13], v190 offset:0x2e00
	v_mfma_f32_32x32x16_bf16 v[32:47], v[92:95], v[162:165], v[32:47]
	ds_read_b64_tr_b16 v[162:163], v190 offset:0x3600
	ds_read_b64_tr_b16 v[164:165], v190 offset:0x3e00
	global_load_dwordx4 v[152:155], v198, s[100:101]
	global_load_dwordx4 v[148:151], v199, s[100:101]
	global_load_dwordx4 v[144:147], v0, s[100:101] offset:2048
	s_add_u32 s100, s100, 0x1a0000
	s_addc_u32 s101, s101, 0
	s_waitcnt lgkmcnt(8)
	v_mfma_f32_32x32x16_bf16 v[48:63], v[80:83], v[210:213], v[48:63]
	v_mfma_f32_32x32x16_bf16 v[48:63], v[84:87], v[214:217], v[48:63]
	v_mfma_f32_32x32x16_bf16 v[48:63], v[88:91], v[244:247], v[48:63]
	v_mfma_f32_32x32x16_bf16 v[48:63], v[92:95], v[248:251], v[48:63]
	s_waitcnt lgkmcnt(0)
	v_mfma_f32_32x32x16_bf16 v[64:79], v[80:83], v[2:5], v[64:79]
	v_mfma_f32_32x32x16_bf16 v[64:79], v[84:87], v[6:9], v[64:79]
	v_mfma_f32_32x32x16_bf16 v[64:79], v[88:91], v[10:13], v[64:79]
	v_mfma_f32_32x32x16_bf16 v[64:79], v[92:95], v[162:165], v[64:79]
	s_setprio 0
	s_barrier
; #define A128_SBAR() __builtin_amdgcn_sched_barrier(0)
; #define A128_PK4(P, BASE, OUT) do { u32x4 w = {cvt_pk_bf16(P[BASE + 0], P[BASE + 1]), cvt_pk_bf16(P[BASE + 2], P[BASE + 3]), cvt_pk_bf16(P[BASE + 4], P[BASE + 5]), cvt_pk_bf16(P[BASE + 6], P[BASE + 7])}; \
;     OUT = __builtin_bit_cast(bf16x8, w); } while (0)
; #define A128_SWAIT() asm volatile("s_waitcnt vmcnt(3)" ::: "memory")
; __device__ __forceinline__ void finishSM(f32x16& p0, f32x16& p1, float alpha, float& l_reg, bf16x8& pa0, bf16x8& pa1, bf16x8& pa2, bf16x8& pa3) {
; #pragma unroll
;   for (int r = 0; r < 16; ++r) p1[r] = __builtin_amdgcn_exp2f(p1[r]);
;   typedef float f32x8_ __attribute__((ext_vector_type(8))); typedef float f32x2_ __attribute__((ext_vector_type(2)));
;   const f32x16 s16_ = p0 + p1; const f32x8_ s8_ = s16_.lo + s16_.hi; const f32x4 s4_ = s8_.lo + s8_.hi; const f32x2_ s2_ = s4_.lo + s4_.hi;
;   float ps = s2_.x + s2_.y;
;   { auto rr = __builtin_amdgcn_permlane32_swap(__float_as_uint(ps), __float_as_uint(ps), false, false); ps = __uint_as_float(rr[0]) + __uint_as_float(rr[1]); }
;   l_reg = l_reg * alpha + ps;
;     ...
;   A128_PK4(p0, 0, pa0); A128_PK4(p0, 8, pa1); A128_PK4(p1, 0, pa2); A128_PK4(p1, 8, pa3);
;     ...
; }
; __device__ __forceinline__ void unit(const bf16* __restrict__ Qb0, const bf16* __restrict__ Kh0, const bf16* __restrict__ Vh, bf16_t* Ob, int seq, char* lds, const int tid_in, const float lam, const float onem, const float* __restrict__ subw, const float* __restrict__ kmb  ) {
;     ...
;   for (int j = 1; j + 1 < NT; j += 2) {
;     A128_SBAR(); qkt(pB0, pB1, K_lds + SHM_K, qr, r32, hi);
;     finishSM(pA0, pA1, alA, l_reg, pa0, pa1, pa2, pa3); A128_SBAR();
;     A128_SLOAD(1, (j + 2) * KVBLK); A128_SBAR();
;     pv_d0(o, vb0, pa0, pa1, pa2, pa3); partialSM(pB0, pB1, m_reg, mnB, alB, nomax);
;     __syncthreads(); A128_SWAIT(); A128_SWRITE(0, 0);
;     if (!nomax) A128_RESC(alB); __syncthreads();
;     A128_SBAR(); qkt(pA0, pA1, K_lds, qr, r32, hi);
;     finishSM(pB0, pB1, alB, l_reg, pa0, pa1, pa2, pa3); A128_SBAR();
;     if (j + 3 < NT) A128_SLOAD(0, (j + 3) * KVBLK); A128_SBAR();
;     pv_d0(o, vb0 + (int)SHM_V, pa0, pa1, pa2, pa3); partialSM(pA0, pA1, m_reg, mnA, alA, nomax);
;     __syncthreads(); A128_SWAIT(); A128_SWRITE(1, 1);
;     if (!nomax) A128_RESC(alA); __syncthreads();
;   }
	v_exp_f32_e32 v96, v96
	v_exp_f32_e32 v97, v97
	v_exp_f32_e32 v98, v98
	v_exp_f32_e32 v99, v99
	v_exp_f32_e32 v100, v100
	v_exp_f32_e32 v101, v101
	v_exp_f32_e32 v102, v102
	v_exp_f32_e32 v103, v103
	v_exp_f32_e32 v104, v104
	v_exp_f32_e32 v105, v105
	v_exp_f32_e32 v106, v106
	v_exp_f32_e32 v107, v107
	v_exp_f32_e32 v108, v108
	v_exp_f32_e32 v109, v109
	v_exp_f32_e32 v110, v110
	v_exp_f32_e32 v111, v111
	v_exp_f32_e32 v112, v112
	v_exp_f32_e32 v113, v113
	v_exp_f32_e32 v114, v114
	v_exp_f32_e32 v115, v115
	v_exp_f32_e32 v116, v116
	v_exp_f32_e32 v117, v117
	v_exp_f32_e32 v118, v118
	v_exp_f32_e32 v119, v119
	v_exp_f32_e32 v120, v120
	v_exp_f32_e32 v121, v121
	v_exp_f32_e32 v122, v122
	v_exp_f32_e32 v123, v123
	v_exp_f32_e32 v124, v124
	v_exp_f32_e32 v125, v125
	v_exp_f32_e32 v126, v126
	v_exp_f32_e32 v127, v127
	v_pk_add_f32 v[2:3], v[112:113], v[96:97]
	v_pk_add_f32 v[4:5], v[114:115], v[98:99]
	v_pk_add_f32 v[6:7], v[116:117], v[100:101]
	v_pk_add_f32 v[8:9], v[118:119], v[102:103]
	v_pk_add_f32 v[10:11], v[120:121], v[104:105]
	v_pk_add_f32 v[12:13], v[122:123], v[106:107]
	v_pk_add_f32 v[196:197], v[124:125], v[108:109]
	v_pk_add_f32 v[194:195], v[126:127], v[110:111]
	v_pk_add_f32 v[2:3], v[2:3], v[10:11]
	v_pk_add_f32 v[4:5], v[4:5], v[12:13]
	v_pk_add_f32 v[6:7], v[6:7], v[196:197]
	v_pk_add_f32 v[8:9], v[8:9], v[194:195]
	v_pk_add_f32 v[2:3], v[2:3], v[6:7]
	v_pk_add_f32 v[4:5], v[4:5], v[8:9]
	s_nop 0
	v_pk_add_f32 v[2:3], v[2:3], v[4:5]
	s_nop 0
	v_pk_add_f32 v[14:15], v[14:15], v[2:3]
	v_cvt_pk_bf16_f32 v80, v112, v113
	v_cvt_pk_bf16_f32 v81, v114, v115
	v_cvt_pk_bf16_f32 v82, v116, v117
	v_cvt_pk_bf16_f32 v83, v118, v119
	v_cvt_pk_bf16_f32 v84, v120, v121
	v_cvt_pk_bf16_f32 v85, v122, v123
	v_cvt_pk_bf16_f32 v86, v124, v125
	v_cvt_pk_bf16_f32 v87, v126, v127
	v_cvt_pk_bf16_f32 v88, v96, v97
	v_cvt_pk_bf16_f32 v89, v98, v99
	v_cvt_pk_bf16_f32 v90, v100, v101
	v_cvt_pk_bf16_f32 v91, v102, v103
	v_cvt_pk_bf16_f32 v92, v104, v105
	v_cvt_pk_bf16_f32 v93, v106, v107
	v_cvt_pk_bf16_f32 v94, v108, v109
	v_cvt_pk_bf16_f32 v95, v110, v111
	s_barrier
	s_setprio 1
	ds_read_b128 v[2:5], v204 offset:32768
	ds_read_b128 v[6:9], v204 offset:36864
	ds_read_b128 v[10:13], v205 offset:32768
	ds_read_b128 v[162:165], v205 offset:36864
	s_waitcnt lgkmcnt(2)
	v_mfma_f32_32x32x16_bf16 v[112:127], v[2:5], v[140:143], 0
	ds_read_b128 v[168:171], v192 offset:32768
	ds_read_b128 v[172:175], v192 offset:36864
	v_mfma_f32_32x32x16_bf16 v[96:111], v[6:9], v[140:143], 0
	ds_read_b128 v[176:179], v193 offset:32768
	ds_read_b128 v[194:197], v193 offset:36864
	s_waitcnt lgkmcnt(4)
	v_mfma_f32_32x32x16_bf16 v[112:127], v[10:13], v[136:139], v[112:127]
	ds_read_b64_tr_b16 v[210:211], v189 offset:0x0
	ds_read_b64_tr_b16 v[212:213], v189 offset:0x800
	ds_read_b64_tr_b16 v[214:215], v189 offset:0x1000
	v_mfma_f32_32x32x16_bf16 v[96:111], v[162:165], v[136:139], v[96:111]
	ds_read_b64_tr_b16 v[216:217], v189 offset:0x1800
	ds_read_b64_tr_b16 v[244:245], v189 offset:0x2000
	ds_read_b64_tr_b16 v[246:247], v189 offset:0x2800
	s_waitcnt lgkmcnt(8)
	v_mfma_f32_32x32x16_bf16 v[112:127], v[168:171], v[132:135], v[112:127]
	ds_read_b64_tr_b16 v[248:249], v189 offset:0x3000
	ds_read_b64_tr_b16 v[250:251], v189 offset:0x3800
	v_mfma_f32_32x32x16_bf16 v[96:111], v[172:175], v[132:135], v[96:111]
	ds_read_b64_tr_b16 v[2:3], v189 offset:0x200
	ds_read_b64_tr_b16 v[4:5], v189 offset:0xa00
	ds_read_b64_tr_b16 v[6:7], v189 offset:0x1200
	s_waitcnt lgkmcnt(11)
	v_mfma_f32_32x32x16_bf16 v[112:127], v[176:179], v[128:131], v[112:127]
	ds_read_b64_tr_b16 v[8:9], v189 offset:0x1a00
	ds_read_b64_tr_b16 v[10:11], v189 offset:0x2200
	ds_read_b64_tr_b16 v[12:13], v189 offset:0x2a00
	v_mfma_f32_32x32x16_bf16 v[96:111], v[194:197], v[128:131], v[96:111]
	ds_read_b64_tr_b16 v[162:163], v189 offset:0x3200
	ds_read_b64_tr_b16 v[164:165], v189 offset:0x3a00
	s_waitcnt vmcnt(3)
	ds_write_b128 v203, v[240:243] offset:40960
	ds_write_b128 v191, v[232:235]
	ds_write_b128 v202, v[236:239]
	s_waitcnt lgkmcnt(11)
	v_mfma_f32_32x32x16_bf16 v[16:31], v[80:83], v[210:213], v[16:31]
	ds_read_b64_tr_b16 v[210:211], v189 offset:0x400
	ds_read_b64_tr_b16 v[212:213], v189 offset:0xc00
	v_mfma_f32_32x32x16_bf16 v[16:31], v[84:87], v[214:217], v[16:31]
	ds_read_b64_tr_b16 v[214:215], v189 offset:0x1400
	ds_read_b64_tr_b16 v[216:217], v189 offset:0x1c00
	v_mfma_f32_32x32x16_bf16 v[16:31], v[88:91], v[244:247], v[16:31]
	ds_read_b64_tr_b16 v[244:245], v189 offset:0x2400
	ds_read_b64_tr_b16 v[246:247], v189 offset:0x2c00
	v_mfma_f32_32x32x16_bf16 v[16:31], v[92:95], v[248:251], v[16:31]
	ds_read_b64_tr_b16 v[248:249], v189 offset:0x3400
	ds_read_b64_tr_b16 v[250:251], v189 offset:0x3c00
	s_waitcnt lgkmcnt(11)
	v_mfma_f32_32x32x16_bf16 v[32:47], v[80:83], v[2:5], v[32:47]
	ds_read_b64_tr_b16 v[2:3], v189 offset:0x600
	ds_read_b64_tr_b16 v[4:5], v189 offset:0xe00
	v_mfma_f32_32x32x16_bf16 v[32:47], v[84:87], v[6:9], v[32:47]
	ds_read_b64_tr_b16 v[6:7], v189 offset:0x1600
	ds_read_b64_tr_b16 v[8:9], v189 offset:0x1e00
	v_mfma_f32_32x32x16_bf16 v[32:47], v[88:91], v[10:13], v[32:47]
	ds_read_b64_tr_b16 v[10:11], v189 offset:0x2600
	ds_read_b64_tr_b16 v[12:13], v189 offset:0x2e00
	v_mfma_f32_32x32x16_bf16 v[32:47], v[92:95], v[162:165], v[32:47]
	ds_read_b64_tr_b16 v[162:163], v189 offset:0x3600
	ds_read_b64_tr_b16 v[164:165], v189 offset:0x3e00
	global_load_dwordx4 v[232:235], v198, s[100:101]
	global_load_dwordx4 v[236:239], v199, s[100:101]
	global_load_dwordx4 v[240:243], v0, s[100:101] offset:2048
	s_add_u32 s100, s100, 0x1a0000
	s_addc_u32 s101, s101, 0
	s_waitcnt lgkmcnt(8)
	v_mfma_f32_32x32x16_bf16 v[48:63], v[80:83], v[210:213], v[48:63]
	v_mfma_f32_32x32x16_bf16 v[48:63], v[84:87], v[214:217], v[48:63]
	v_mfma_f32_32x32x16_bf16 v[48:63], v[88:91], v[244:247], v[48:63]
	v_mfma_f32_32x32x16_bf16 v[48:63], v[92:95], v[248:251], v[48:63]
	s_waitcnt lgkmcnt(0)
	v_mfma_f32_32x32x16_bf16 v[64:79], v[80:83], v[2:5], v[64:79]
	v_mfma_f32_32x32x16_bf16 v[64:79], v[84:87], v[6:9], v[64:79]
	v_mfma_f32_32x32x16_bf16 v[64:79], v[88:91], v[10:13], v[64:79]
	v_mfma_f32_32x32x16_bf16 v[64:79], v[92:95], v[162:165], v[64:79]
	s_setprio 0
	s_barrier
; #define A128_SBAR() __builtin_amdgcn_sched_barrier(0)
; #define A128_SWAIT() asm volatile("s_waitcnt vmcnt(3)" ::: "memory")
; __device__ __forceinline__ void finishSM(f32x16& p0, f32x16& p1, float alpha, float& l_reg, bf16x8& pa0, bf16x8& pa1, bf16x8& pa2, bf16x8& pa3) {
; #pragma unroll
;   for (int r = 0; r < 16; ++r) p1[r] = __builtin_amdgcn_exp2f(p1[r]);
;   typedef float f32x8_ __attribute__((ext_vector_type(8))); typedef float f32x2_ __attribute__((ext_vector_type(2)));
;   const f32x16 s16_ = p0 + p1; const f32x8_ s8_ = s16_.lo + s16_.hi; const f32x4 s4_ = s8_.lo + s8_.hi; const f32x2_ s2_ = s4_.lo + s4_.hi;
;   float ps = s2_.x + s2_.y;
;   { auto rr = __builtin_amdgcn_permlane32_swap(__float_as_uint(ps), __float_as_uint(ps), false, false); ps = __uint_as_float(rr[0]) + __uint_as_float(rr[1]); }
;   l_reg = l_reg * alpha + ps;
; __device__ __forceinline__ void unit(const bf16* __restrict__ Qb0, const bf16* __restrict__ Kh0, const bf16* __restrict__ Vh, bf16_t* Ob, int seq, char* lds, const int tid_in, const float lam, const float onem, const float* __restrict__ subw, const float* __restrict__ kmb  ) {
;     ...
;   for (int j = 1; j + 1 < NT; j += 2) {
;     A128_SBAR(); qkt(pB0, pB1, K_lds + SHM_K, qr, r32, hi);
;     finishSM(pA0, pA1, alA, l_reg, pa0, pa1, pa2, pa3); A128_SBAR();
;     A128_SLOAD(1, (j + 2) * KVBLK); A128_SBAR();
;     pv_d0(o, vb0, pa0, pa1, pa2, pa3); partialSM(pB0, pB1, m_reg, mnB, alB, nomax);
;     __syncthreads(); A128_SWAIT(); A128_SWRITE(0, 0);
;     if (!nomax) A128_RESC(alB); __syncthreads();
;     A128_SBAR(); qkt(pA0, pA1, K_lds, qr, r32, hi);
;     finishSM(pB0, pB1, alB, l_reg, pa0, pa1, pa2, pa3); A128_SBAR();
;     if (j + 3 < NT) A128_SLOAD(0, (j + 3) * KVBLK); A128_SBAR();
;     pv_d0(o, vb0 + (int)SHM_V, pa0, pa1, pa2, pa3); partialSM(pA0, pA1, m_reg, mnA, alA, nomax);
;     __syncthreads(); A128_SWAIT(); A128_SWRITE(1, 1);
;     if (!nomax) A128_RESC(alA); __syncthreads();
;   }
;   A128_SBAR(); qkt(pB0, pB1, K_lds + SHM_K, qr, r32, hi);
;   finishSM(pA0, pA1, alA, l_reg, pa0, pa1, pa2, pa3); A128_SBAR();
;   pv_d0(o, vb0, pa0, pa1, pa2, pa3); partialSM(pB0, pB1, m_reg, mnB, alB, nomax);
;   __syncthreads(); if (!nomax) A128_RESC(alB);
;   finishSM(pB0, pB1, alB, l_reg, pa0, pa1, pa2, pa3); A128_SBAR();
	s_cmp_ge_u32 s38, s27
	s_cbranch_scc1 .Lfa_exit
	s_add_i32 s38, s38, 2
	v_exp_f32_e32 v96, v96
	v_exp_f32_e32 v97, v97
	v_exp_f32_e32 v98, v98
	v_exp_f32_e32 v99, v99
	v_exp_f32_e32 v100, v100
	v_exp_f32_e32 v101, v101
	v_exp_f32_e32 v102, v102
	v_exp_f32_e32 v103, v103
	v_exp_f32_e32 v104, v104
	v_exp_f32_e32 v105, v105
	v_exp_f32_e32 v106, v106
	v_exp_f32_e32 v107, v107
	v_exp_f32_e32 v108, v108
	v_exp_f32_e32 v109, v109
	v_exp_f32_e32 v110, v110
	v_exp_f32_e32 v111, v111
	v_exp_f32_e32 v112, v112
	v_exp_f32_e32 v113, v113
	v_exp_f32_e32 v114, v114
	v_exp_f32_e32 v115, v115
	v_exp_f32_e32 v116, v116
	v_exp_f32_e32 v117, v117
	v_exp_f32_e32 v118, v118
	v_exp_f32_e32 v119, v119
	v_exp_f32_e32 v120, v120
	v_exp_f32_e32 v121, v121
	v_exp_f32_e32 v122, v122
	v_exp_f32_e32 v123, v123
	v_exp_f32_e32 v124, v124
	v_exp_f32_e32 v125, v125
	v_exp_f32_e32 v126, v126
	v_exp_f32_e32 v127, v127
	v_pk_add_f32 v[2:3], v[112:113], v[96:97]
	v_pk_add_f32 v[4:5], v[114:115], v[98:99]
	v_pk_add_f32 v[6:7], v[116:117], v[100:101]
	v_pk_add_f32 v[8:9], v[118:119], v[102:103]
	v_pk_add_f32 v[10:11], v[120:121], v[104:105]
	v_pk_add_f32 v[12:13], v[122:123], v[106:107]
	v_pk_add_f32 v[196:197], v[124:125], v[108:109]
	v_pk_add_f32 v[194:195], v[126:127], v[110:111]
	v_pk_add_f32 v[2:3], v[2:3], v[10:11]
	v_pk_add_f32 v[4:5], v[4:5], v[12:13]
	v_pk_add_f32 v[6:7], v[6:7], v[196:197]
	v_pk_add_f32 v[8:9], v[8:9], v[194:195]
	v_pk_add_f32 v[2:3], v[2:3], v[6:7]
	v_pk_add_f32 v[4:5], v[4:5], v[8:9]
	s_nop 0
	v_pk_add_f32 v[2:3], v[2:3], v[4:5]
	s_nop 0
	v_pk_add_f32 v[14:15], v[14:15], v[2:3]
	v_cvt_pk_bf16_f32 v80, v112, v113
	v_cvt_pk_bf16_f32 v81, v114, v115
	v_cvt_pk_bf16_f32 v82, v116, v117
	v_cvt_pk_bf16_f32 v83, v118, v119
	v_cvt_pk_bf16_f32 v84, v120, v121
	v_cvt_pk_bf16_f32 v85, v122, v123
	v_cvt_pk_bf16_f32 v86, v124, v125
	v_cvt_pk_bf16_f32 v87, v126, v127
	v_cvt_pk_bf16_f32 v88, v96, v97
	v_cvt_pk_bf16_f32 v89, v98, v99
	v_cvt_pk_bf16_f32 v90, v100, v101
	v_cvt_pk_bf16_f32 v91, v102, v103
	v_cvt_pk_bf16_f32 v92, v104, v105
	v_cvt_pk_bf16_f32 v93, v106, v107
	v_cvt_pk_bf16_f32 v94, v108, v109
	v_cvt_pk_bf16_f32 v95, v110, v111
	s_branch .Lfa_loop
.Lfa_exit:
	v_exp_f32_e32 v178, v112
	v_exp_f32_e32 v179, v113
	v_exp_f32_e32 v176, v114
	v_exp_f32_e32 v177, v115
	v_exp_f32_e32 v174, v116
	v_exp_f32_e32 v175, v117
	v_exp_f32_e32 v172, v118
	v_exp_f32_e32 v173, v119
	v_exp_f32_e32 v170, v120
	v_exp_f32_e32 v171, v121
	v_exp_f32_e32 v168, v122
	v_exp_f32_e32 v169, v123
	v_exp_f32_e32 v164, v124
	v_exp_f32_e32 v165, v125
	v_exp_f32_e32 v162, v126
	v_exp_f32_e32 v163, v127
	v_mov_b32_e32 v80, v96
	v_mov_b32_e32 v81, v97
	v_mov_b32_e32 v82, v98
	v_mov_b32_e32 v83, v99
	v_mov_b32_e32 v84, v100
	v_mov_b32_e32 v85, v101
	v_mov_b32_e32 v86, v102
	v_mov_b32_e32 v87, v103
	v_mov_b32_e32 v88, v104
	v_mov_b32_e32 v89, v105
	v_mov_b32_e32 v90, v106
	v_mov_b32_e32 v91, v107
	v_mov_b32_e32 v92, v108
	v_mov_b32_e32 v93, v109
	v_mov_b32_e32 v94, v110
	v_mov_b32_e32 v95, v111
	v_add_f32_e32 v14, v14, v15
	s_nop 0
	v_mov_b32_e32 v15, v14
	s_nop 1
	v_permlane32_swap_b32_e32 v14, v15
	s_nop 1
	v_add_f32_e32 v14, v14, v15
	s_nop 0
	v_add_f32_e32 v186, v186, v14
	v_mov_b32_e32 v15, 1.0
	s_mov_b64 s[4:5], -1
	s_mov_b64 s[2:3], -1
	s_cmp_ge_u32 s37, 0x400
	s_cbranch_scc1 .Lfa_x1
	s_barrier
